# strategy 7 continued: same f32->bf16 RNE instruction selection (v_cvt_pk_bf16_f32 + ds_write_b16) also in the phase-4 level-1 task blocks (276 sites total)
# baseline (speedup 1.0000x reference)
.LBB0_806:
	s_mov_b64 s[2:3], -1
	s_and_b64 vcc, exec, s[40:41]
	s_cbranch_vccz .LBB0_808
	s_and_b32 s2, s54, 0xffffffc0
	v_mul_u32_u24_e32 v66, 0x440, v186
	v_lshlrev_b32_e32 v67, 1, v185
	s_add_i32 s2, s2, 0
	v_add3_u32 v66, s2, v66, v67
	v_bfe_u32 v68, v18, 16, 1
	s_movk_i32 s2, 0x7fff
	v_add3_u32 v68, v18, v68, s2
	s_barrier
	ds_write_b16_d16_hi v66, v68 offset:49152
	v_cvt_pk_bf16_f32 v68, v19, v19
	ds_write_b16 v66, v68 offset:49424
	v_cvt_pk_bf16_f32 v68, v20, v20
	ds_write_b16 v66, v68 offset:49696
	v_cvt_pk_bf16_f32 v68, v21, v21
	ds_write_b16 v66, v68 offset:49968
	v_cvt_pk_bf16_f32 v68, v22, v22
	ds_write_b16 v66, v68 offset:51328
	v_cvt_pk_bf16_f32 v68, v23, v23
	ds_write_b16 v66, v68 offset:51600
	v_cvt_pk_bf16_f32 v68, v24, v24
	ds_write_b16 v66, v68 offset:51872
	v_cvt_pk_bf16_f32 v68, v25, v25
	ds_write_b16 v66, v68 offset:52144
	v_cvt_pk_bf16_f32 v68, v26, v26
	ds_write_b16 v66, v68 offset:53504
	v_cvt_pk_bf16_f32 v68, v27, v27
	ds_write_b16 v66, v68 offset:53776
	v_cvt_pk_bf16_f32 v68, v28, v28
	ds_write_b16 v66, v68 offset:54048
	v_cvt_pk_bf16_f32 v68, v29, v29
	ds_write_b16 v66, v68 offset:54320
	v_cvt_pk_bf16_f32 v68, v30, v30
	ds_write_b16 v66, v68 offset:55680
	v_cvt_pk_bf16_f32 v68, v31, v31
	ds_write_b16 v66, v68 offset:55952
	v_cvt_pk_bf16_f32 v68, v32, v32
	ds_write_b16 v66, v68 offset:56224
	v_cvt_pk_bf16_f32 v68, v33, v33
	ds_write_b16 v66, v68 offset:56496
	v_cvt_pk_bf16_f32 v68, v34, v34
	ds_write_b16 v66, v68 offset:57856
	v_cvt_pk_bf16_f32 v68, v35, v35
	ds_write_b16 v66, v68 offset:58128
	v_cvt_pk_bf16_f32 v68, v36, v36
	ds_write_b16 v66, v68 offset:58400
	v_cvt_pk_bf16_f32 v68, v37, v37
	ds_write_b16 v66, v68 offset:58672
	v_cvt_pk_bf16_f32 v68, v38, v38
	ds_write_b16 v66, v68 offset:60032
	v_cvt_pk_bf16_f32 v68, v39, v39
	ds_write_b16 v66, v68 offset:60304
	v_cvt_pk_bf16_f32 v68, v40, v40
	ds_write_b16 v66, v68 offset:60576
	v_cvt_pk_bf16_f32 v68, v41, v41
	ds_write_b16 v66, v68 offset:60848
	v_cvt_pk_bf16_f32 v68, v42, v42
	ds_write_b16 v66, v68 offset:62208
	v_cvt_pk_bf16_f32 v68, v43, v43
	ds_write_b16 v66, v68 offset:62480
	v_cvt_pk_bf16_f32 v68, v44, v44
	ds_write_b16 v66, v68 offset:62752
	v_cvt_pk_bf16_f32 v68, v45, v45
	ds_write_b16 v66, v68 offset:63024
	v_cvt_pk_bf16_f32 v68, v46, v46
	ds_write_b16 v66, v68 offset:64384
	v_cvt_pk_bf16_f32 v68, v47, v47
	ds_write_b16 v66, v68 offset:64656
	v_cvt_pk_bf16_f32 v68, v48, v48
	ds_write_b16 v66, v68 offset:64928
	v_cvt_pk_bf16_f32 v68, v49, v49
	v_add_u32_e32 v67, 0xc000, v66
	ds_write_b16 v66, v68 offset:65200
	v_cvt_pk_bf16_f32 v66, v50, v50
	ds_write_b16 v67, v66 offset:17408
	v_cvt_pk_bf16_f32 v66, v51, v51
	ds_write_b16 v67, v66 offset:17680
	v_cvt_pk_bf16_f32 v66, v52, v52
	ds_write_b16 v67, v66 offset:17952
	v_cvt_pk_bf16_f32 v66, v53, v53
	ds_write_b16 v67, v66 offset:18224
	v_cvt_pk_bf16_f32 v66, v54, v54
	ds_write_b16 v67, v66 offset:19584
	v_cvt_pk_bf16_f32 v66, v55, v55
	ds_write_b16 v67, v66 offset:19856
	v_cvt_pk_bf16_f32 v66, v56, v56
	ds_write_b16 v67, v66 offset:20128
	v_cvt_pk_bf16_f32 v66, v57, v57
	ds_write_b16 v67, v66 offset:20400
	v_cvt_pk_bf16_f32 v66, v58, v58
	ds_write_b16 v67, v66 offset:21760
	v_cvt_pk_bf16_f32 v66, v59, v59
	ds_write_b16 v67, v66 offset:22032
	v_cvt_pk_bf16_f32 v66, v60, v60
	ds_write_b16 v67, v66 offset:22304
	v_cvt_pk_bf16_f32 v66, v61, v61
	ds_write_b16 v67, v66 offset:22576
	v_cvt_pk_bf16_f32 v66, v62, v62
	ds_write_b16 v67, v66 offset:23936
	v_cvt_pk_bf16_f32 v66, v63, v63
	ds_write_b16 v67, v66 offset:24208
	v_cvt_pk_bf16_f32 v66, v64, v64
	ds_write_b16 v67, v66 offset:24480
	v_cvt_pk_bf16_f32 v66, v65, v65
	ds_write_b16 v67, v66 offset:24752
	v_cvt_pk_bf16_f32 v66, v2, v2
	ds_write_b16 v67, v66 offset:26112
	v_cvt_pk_bf16_f32 v66, v3, v3
	ds_write_b16 v67, v66 offset:26384
	v_cvt_pk_bf16_f32 v66, v4, v4
	ds_write_b16 v67, v66 offset:26656
	v_cvt_pk_bf16_f32 v66, v5, v5
	ds_write_b16 v67, v66 offset:26928
	v_cvt_pk_bf16_f32 v66, v6, v6
	ds_write_b16 v67, v66 offset:28288
	v_cvt_pk_bf16_f32 v66, v7, v7
	ds_write_b16 v67, v66 offset:28560
	v_cvt_pk_bf16_f32 v66, v8, v8
	ds_write_b16 v67, v66 offset:28832
	v_cvt_pk_bf16_f32 v66, v9, v9
	ds_write_b16 v67, v66 offset:29104
	v_cvt_pk_bf16_f32 v66, v10, v10
	ds_write_b16 v67, v66 offset:30464
	v_cvt_pk_bf16_f32 v66, v11, v11
	ds_write_b16 v67, v66 offset:30736
	v_cvt_pk_bf16_f32 v66, v12, v12
	ds_write_b16 v67, v66 offset:31008
	v_cvt_pk_bf16_f32 v66, v13, v13
	ds_write_b16 v67, v66 offset:31280
	v_cvt_pk_bf16_f32 v66, v14, v14
	ds_write_b16 v67, v66 offset:32640
	v_cvt_pk_bf16_f32 v66, v15, v15
	ds_write_b16 v67, v66 offset:32912
	v_cvt_pk_bf16_f32 v66, v16, v16
	ds_write_b16 v67, v66 offset:33184
	v_cvt_pk_bf16_f32 v66, v17, v17
	v_readlane_b32 s3, v254, 27
	ds_write_b16 v67, v66 offset:33456
	s_movk_i32 s2, 0x110
	v_lshl_or_b32 v66, s3, 5, v185
	v_mul_lo_u32 v66, v66, s2
	v_lshlrev_b32_e32 v67, 3, v186
	s_waitcnt lgkmcnt(0)
	v_add3_u32 v66, 0, v66, v67
	s_barrier
	v_add_u32_e32 v82, 0xc000, v66
	v_lshl_or_b32 v74, s3, 13, v178
	ds_read2_b64 v[66:69], v82 offset1:2
	ds_read2_b64 v[70:73], v82 offset0:4 offset1:6
	v_ashrrev_i32_e32 v75, 31, v74
	v_lshl_add_u64 v[78:79], s[42:43], 0, v[74:75]
	s_mov_b64 s[2:3], 0x8000
	v_lshl_add_u64 v[86:87], v[78:79], 0, s[2:3]
	s_mov_b32 s2, 0x9000
	ds_read2_b64 v[74:77], v82 offset0:8 offset1:10
	v_add_co_u32_e32 v88, vcc, s2, v78
	s_mov_b64 s[2:3], 0
	s_nop 0
	v_addc_co_u32_e32 v89, vcc, 0, v79, vcc
	s_waitcnt lgkmcnt(2)
	global_store_dwordx4 v[88:89], v[66:69], off offset:-4096 sc1
	s_waitcnt lgkmcnt(1)
	global_store_dwordx4 v[86:87], v[70:73], off offset:1024 sc1
	s_waitcnt lgkmcnt(0)
	global_store_dwordx4 v[86:87], v[74:77], off offset:2048 sc1
	ds_read2_b64 v[66:69], v82 offset0:12 offset1:14
	ds_read2_b64 v[70:73], v82 offset0:16 offset1:18
	ds_read2_b64 v[74:77], v82 offset0:20 offset1:22
	ds_read2_b64 v[78:81], v82 offset0:24 offset1:26
	ds_read2_b64 v[82:85], v82 offset0:28 offset1:30
	s_waitcnt lgkmcnt(4)
	global_store_dwordx4 v[86:87], v[66:69], off offset:3072 sc1
	s_waitcnt lgkmcnt(3)
	global_store_dwordx4 v[88:89], v[70:73], off sc1
	s_waitcnt lgkmcnt(2)
	global_store_dwordx4 v[88:89], v[74:77], off offset:1024 sc1
	s_waitcnt lgkmcnt(1)
	global_store_dwordx4 v[88:89], v[78:81], off offset:2048 sc1
	s_waitcnt lgkmcnt(0)
	global_store_dwordx4 v[88:89], v[82:85], off offset:3072 sc1
	s_waitcnt lgkmcnt(0)
	s_barrier

.LBB0_818:
	s_and_b32 s2, s54, 0xffffffc0
	v_mul_u32_u24_e32 v66, 0x440, v186
	v_lshlrev_b32_e32 v67, 1, v185
	s_add_i32 s2, s2, s48
	v_add3_u32 v66, s2, v66, v67
	v_bfe_u32 v67, v18, 16, 1
	s_movk_i32 s2, 0x7fff
	v_add3_u32 v67, v18, v67, s2
	ds_write_b16_d16_hi v66, v67
	v_cvt_pk_bf16_f32 v67, v19, v19
	ds_write_b16 v66, v67 offset:272
	v_cvt_pk_bf16_f32 v67, v20, v20
	ds_write_b16 v66, v67 offset:544
	v_cvt_pk_bf16_f32 v67, v21, v21
	ds_write_b16 v66, v67 offset:816
	v_cvt_pk_bf16_f32 v67, v22, v22
	ds_write_b16 v66, v67 offset:2176
	v_cvt_pk_bf16_f32 v67, v23, v23
	ds_write_b16 v66, v67 offset:2448
	v_cvt_pk_bf16_f32 v67, v24, v24
	ds_write_b16 v66, v67 offset:2720
	v_cvt_pk_bf16_f32 v67, v25, v25
	ds_write_b16 v66, v67 offset:2992
	v_cvt_pk_bf16_f32 v67, v26, v26
	ds_write_b16 v66, v67 offset:4352
	v_cvt_pk_bf16_f32 v67, v27, v27
	ds_write_b16 v66, v67 offset:4624
	v_cvt_pk_bf16_f32 v67, v28, v28
	ds_write_b16 v66, v67 offset:4896
	v_cvt_pk_bf16_f32 v67, v29, v29
	ds_write_b16 v66, v67 offset:5168
	v_cvt_pk_bf16_f32 v67, v30, v30
	ds_write_b16 v66, v67 offset:6528
	v_cvt_pk_bf16_f32 v67, v31, v31
	ds_write_b16 v66, v67 offset:6800
	v_cvt_pk_bf16_f32 v67, v32, v32
	ds_write_b16 v66, v67 offset:7072
	v_cvt_pk_bf16_f32 v67, v33, v33
	ds_write_b16 v66, v67 offset:7344
	v_cvt_pk_bf16_f32 v67, v34, v34
	ds_write_b16 v66, v67 offset:8704
	v_cvt_pk_bf16_f32 v67, v35, v35
	ds_write_b16 v66, v67 offset:8976
	v_cvt_pk_bf16_f32 v67, v36, v36
	ds_write_b16 v66, v67 offset:9248
	v_cvt_pk_bf16_f32 v67, v37, v37
	ds_write_b16 v66, v67 offset:9520
	v_cvt_pk_bf16_f32 v67, v38, v38
	ds_write_b16 v66, v67 offset:10880
	v_cvt_pk_bf16_f32 v67, v39, v39
	ds_write_b16 v66, v67 offset:11152
	v_cvt_pk_bf16_f32 v67, v40, v40
	ds_write_b16 v66, v67 offset:11424
	v_cvt_pk_bf16_f32 v67, v41, v41
	ds_write_b16 v66, v67 offset:11696
	v_cvt_pk_bf16_f32 v67, v42, v42
	ds_write_b16 v66, v67 offset:13056
	v_cvt_pk_bf16_f32 v67, v43, v43
	ds_write_b16 v66, v67 offset:13328
	v_cvt_pk_bf16_f32 v67, v44, v44
	ds_write_b16 v66, v67 offset:13600
	v_cvt_pk_bf16_f32 v67, v45, v45
	ds_write_b16 v66, v67 offset:13872
	v_cvt_pk_bf16_f32 v67, v46, v46
	ds_write_b16 v66, v67 offset:15232
	v_cvt_pk_bf16_f32 v67, v47, v47
	ds_write_b16 v66, v67 offset:15504
	v_cvt_pk_bf16_f32 v67, v48, v48
	ds_write_b16 v66, v67 offset:15776
	v_cvt_pk_bf16_f32 v67, v49, v49
	ds_write_b16 v66, v67 offset:16048
	v_cvt_pk_bf16_f32 v67, v50, v50
	ds_write_b16 v66, v67 offset:17408
	v_cvt_pk_bf16_f32 v67, v51, v51
	ds_write_b16 v66, v67 offset:17680
	v_cvt_pk_bf16_f32 v67, v52, v52
	ds_write_b16 v66, v67 offset:17952
	v_cvt_pk_bf16_f32 v67, v53, v53
	ds_write_b16 v66, v67 offset:18224
	v_cvt_pk_bf16_f32 v67, v54, v54
	ds_write_b16 v66, v67 offset:19584
	v_cvt_pk_bf16_f32 v67, v55, v55
	ds_write_b16 v66, v67 offset:19856
	v_cvt_pk_bf16_f32 v67, v56, v56
	ds_write_b16 v66, v67 offset:20128
	v_cvt_pk_bf16_f32 v67, v57, v57
	ds_write_b16 v66, v67 offset:20400
	v_cvt_pk_bf16_f32 v67, v58, v58
	ds_write_b16 v66, v67 offset:21760
	v_cvt_pk_bf16_f32 v67, v59, v59
	ds_write_b16 v66, v67 offset:22032
	v_cvt_pk_bf16_f32 v67, v60, v60
	ds_write_b16 v66, v67 offset:22304
	v_cvt_pk_bf16_f32 v67, v61, v61
	ds_write_b16 v66, v67 offset:22576
	v_cvt_pk_bf16_f32 v67, v62, v62
	ds_write_b16 v66, v67 offset:23936
	v_cvt_pk_bf16_f32 v67, v63, v63
	ds_write_b16 v66, v67 offset:24208
	v_cvt_pk_bf16_f32 v67, v64, v64
	ds_write_b16 v66, v67 offset:24480
	v_cvt_pk_bf16_f32 v67, v65, v65
	ds_write_b16 v66, v67 offset:24752
	v_cvt_pk_bf16_f32 v67, v2, v2
	ds_write_b16 v66, v67 offset:26112
	v_cvt_pk_bf16_f32 v67, v3, v3
	ds_write_b16 v66, v67 offset:26384
	v_cvt_pk_bf16_f32 v67, v4, v4
	ds_write_b16 v66, v67 offset:26656
	v_cvt_pk_bf16_f32 v67, v5, v5
	ds_write_b16 v66, v67 offset:26928
	v_cvt_pk_bf16_f32 v67, v6, v6
	ds_write_b16 v66, v67 offset:28288
	v_cvt_pk_bf16_f32 v67, v7, v7
	ds_write_b16 v66, v67 offset:28560
	v_cvt_pk_bf16_f32 v67, v8, v8
	ds_write_b16 v66, v67 offset:28832
	v_cvt_pk_bf16_f32 v67, v9, v9
	ds_write_b16 v66, v67 offset:29104
	v_cvt_pk_bf16_f32 v67, v10, v10
	ds_write_b16 v66, v67 offset:30464
	v_cvt_pk_bf16_f32 v67, v11, v11
	ds_write_b16 v66, v67 offset:30736
	v_cvt_pk_bf16_f32 v67, v12, v12
	ds_write_b16 v66, v67 offset:31008
	v_cvt_pk_bf16_f32 v67, v13, v13
	ds_write_b16 v66, v67 offset:31280
	v_cvt_pk_bf16_f32 v67, v14, v14
	ds_write_b16 v66, v67 offset:32640
	v_cvt_pk_bf16_f32 v67, v15, v15
	ds_write_b16 v66, v67 offset:32912
	v_cvt_pk_bf16_f32 v67, v16, v16
	ds_write_b16 v66, v67 offset:33184
	v_bfe_u32 v67, v17, 16, 1
	v_add3_u32 v67, v17, v67, s2
	ds_write_b16_d16_hi v66, v67 offset:33456
	s_cbranch_execz .LBB0_665
	s_branch .LBB0_666
